# out-proj and down phases: XCD groups (xcc_id&3) start 3us apart so the residual read / XB write bursts of their epilogues do not coincide
# baseline (speedup 1.0000x reference)
; #define PG8_BAR __builtin_amdgcn_s_barrier()
; #define LWS(name) size_t name##_z = 0; asm volatile("" : "+s"(name##_z)); unsigned char* name = p.ws + name##_z
; template <class Epi, class Sched, bool ALIGN_EPI = false, bool SP2 = false>
; __device__ __forceinline__ void gemm_phase(PG8_LAS unsigned char* lds, const Gemm g, const Sched& S, const Epi& E) {
;     int tid_l = pg8_tid(lds); asm volatile("" : "+v"(tid_l));
;     const int tid = tid_l, wid = __builtin_amdgcn_readfirstlane(tid >> 6), lane = tid & 63, wr = wid >> 2, wc = wid & 3, fr = lane & 15, fq = lane >> 4;
;     const int K = g.K, nt = K / BK;
;     unsigned voffA[2], voffB[2];
; #pragma unroll
;     for (int i = 0; i < 2; ++i) { int R, C; stage_rc(tid * 16 + i * 8192, R, C); const int Rb = Epi::PERM ? ((R & ~31) + perm32(R & 31)) : R;
;         voffA[i] = (unsigned)(R * K + C) * 2u; voffB[i] = (unsigned)(Rb * K + C) * 2u; }
;     const size_t kstep = (size_t)(BK * 2);
;     const size_t hstep = (size_t)HALF * K * 2;
;     const size_t tstep = 2 * hstep;
;     const unsigned ldsw = (unsigned)wid * 1024u;
;     const int aoff = lds_byte(wr * 64 + fr, fq * 8), boff = lds_byte(wc * 32 + fr, fq * 8);
;     ...
;     Unit cur, nxt; int ui = 0;
;     if (!S.next(0, cur)) return;
;     f32x4 acc[2][2][4][2];
; #pragma unroll
;     for (int a = 0; a < 2; ++a)
; #pragma unroll
;         for (int b = 0; b < 2; ++b)
; #pragma unroll
;             for (int m = 0; m < 4; ++m)
; #pragma unroll
;                 for (int n = 0; n < 2; ++n) acc[a][b][m][n] = (f32x4){0.f, 0.f, 0.f, 0.f};
;     bf16x8 At[4][2], B0[2][2], B1[2][2];
;     const char* cA = (const char*)g.A + (size_t)cur.pm * tstep; const char* cB = (const char*)g.Bt + (size_t)cur.pn * tstep;
;     S.a_ready(cur);
;     if constexpr (SP2) {
;         PG8_STAGE(PG8_SB(0, 0), cB, voffB); PG8_STAGE(PG8_SB(0, 1), cB + hstep, voffB); PG8_STAGE(PG8_SA(0, 0), cA, voffA); PG8_STAGE(PG8_SA(0, 1), cA + hstep, voffA);
;         if (wr == 1) PG8_BAR;
; __global__ void __launch_bounds__(512, 2) fwd_megakernel(Params p) {
;     ...
;             LWS(ws);
;             pg8::Gemm g{(const bf16_t*)(ws + WS_MIX), (const bf16_t*)(ws + WS_WOUT) + (size_t)l * DM * DM, MP, DM, DM}; pg8::StaticOrder S; S.init(MP, DM, G, bx);
;             EpiResid E{nullptr, (bf16_t*)(ws + WS_XB), (float*)(ws + WS_SSQB)};
;             pg8::gemm_phase<EpiResid, pg8::StaticOrder, true, true>(lds, g, S, E);
.LBB0_1667:
	s_or_b64 exec, exec, s[6:7]
	s_mov_b64 s[8:9], 0
	s_waitcnt lgkmcnt(0)
	s_barrier
	s_getreg_b32 s100, hwreg(HW_REG_XCC_ID, 0, 4)
	s_and_b32 s100, s100, 3
	s_mul_i32 s100, s100, 300
	s_memrealtime s[0:1]
	s_waitcnt lgkmcnt(0)
	s_add_u32 s100, s100, s0
.Lstagger_op:
	s_memrealtime s[0:1]
	s_waitcnt lgkmcnt(0)
	s_sub_u32 s1, s100, s0
	s_cmp_gt_i32 s1, 0
	s_cbranch_scc1 .Lstagger_op
	s_getreg_b32 s0, hwreg(HW_REG_HW_ID, 0, 6)
	s_and_b32 s0, s0, 63
	s_lshl_b32 s0, s0, 2
	s_add_i32 s0, s0, 0
	s_add_i32 s0, s0, 0x20100
	v_mov_b32_e32 v1, s0
	ds_read_b32 v1, v1
	s_waitcnt lgkmcnt(0)
	v_readfirstlane_b32 s0, v1
	s_nop 1
	v_lshl_add_u32 v18, s0, 6, v190
	v_readlane_b32 s0, v254, 43
	v_readlane_b32 s1, v254, 44
	s_andn2_b64 vcc, exec, s[0:1]
	v_readfirstlane_b32 s10, v18
	v_cndmask_b32_e64 v1, 0, 1, s[0:1]
	v_cmp_ne_u32_e64 s[6:7], 1, v1
	s_cbranch_vccnz .LBB0_1703
	v_lshlrev_b32_e32 v1, 4, v18
	v_add_u32_e32 v2, 0x2000, v1
	v_ashrrev_i32_e32 v3, 31, v2
	v_lshrrev_b32_e32 v3, 22, v3
	v_add_u32_e32 v3, v2, v3
	v_ashrrev_i32_e32 v10, 10, v3
	v_mul_i32_i24_e32 v3, 0x400, v10
	v_sub_u32_e32 v2, v2, v3
	v_lshrrev_b32_e32 v3, 4, v2
	v_bitop3_b32 v2, v3, v2, 32 bitop3:0x6c
	v_ashrrev_i32_e32 v3, 31, v2
	v_lshrrev_b32_e32 v3, 26, v3
	v_add_u32_e32 v3, v2, v3
	v_ashrrev_i32_e32 v11, 6, v3
	v_and_b32_e32 v3, 0xc0, v3
	v_sub_u32_e32 v2, v2, v3
	v_ashrrev_i16_sdwa v2, v197, sext(v2) dst_sel:DWORD dst_unused:UNUSED_PAD src0_sel:DWORD src1_sel:BYTE_0
	v_bfe_i32 v13, v2, 0, 16
	v_bfe_i32 v2, v18, 27, 1
	v_lshrrev_b32_e32 v2, 22, v2
	v_add_u32_e32 v2, v1, v2
	s_add_u32 s11, s58, s8
	v_and_b32_e32 v2, 0xfffffc00, v2
	s_addc_u32 s9, s59, s9
	v_sub_u32_e32 v1, v1, v2
	s_add_u32 s0, s11, 0x2c300000
	v_lshrrev_b32_e32 v2, 4, v1
	s_addc_u32 s1, s9, 0
	s_lshl_b64 s[4:5], s[92:93], 21
	v_bitop3_b32 v1, v2, v1, 32 bitop3:0x6c
	v_ashrrev_i32_e32 v3, 31, v18
	s_add_u32 s4, s11, s4
	v_lshlrev_b32_e32 v4, 3, v10
	v_ashrrev_i32_e32 v2, 31, v1
	v_lshrrev_b32_e32 v3, 26, v3
	s_addc_u32 s5, s9, s5
	v_and_b32_e32 v4, 0x1ffff0, v4
	v_lshlrev_b32_e32 v5, 5, v10
	v_lshrrev_b32_e32 v2, 26, v2
	v_add_u32_e32 v3, v18, v3
	s_add_u32 s38, s4, 0x800000
	v_add_u32_e32 v4, v11, v4
	v_and_b32_e32 v12, 32, v5
	v_add_u32_e32 v2, v1, v2
	v_ashrrev_i32_e32 v15, 6, v3
	s_addc_u32 s39, s5, 0
	s_ashr_i32 s18, s10, 6
	v_lshl_or_b32 v4, v4, 10, v12
	v_ashrrev_i32_e32 v14, 6, v2
	v_lshlrev_b32_e32 v3, 3, v15
	v_and_b32_e32 v2, 0xc0, v2
	s_ashr_i32 s8, s10, 8
	s_lshl_b32 s40, s18, 10
	v_add_lshl_u32 v150, v4, v13, 1
	v_and_b32_e32 v3, 0x1ffff0, v3
	v_lshlrev_b32_e32 v4, 5, v15
	v_sub_u32_e32 v1, v1, v2
	v_readlane_b32 s4, v254, 60
	v_add_u32_e32 v3, v14, v3
	v_and_b32_e32 v16, 32, v4
	v_ashrrev_i16_sdwa v1, v197, sext(v1) dst_sel:DWORD dst_unused:UNUSED_PAD src0_sel:DWORD src1_sel:BYTE_0
	v_readlane_b32 s5, v254, 61
	s_add_u32 s30, s38, s4
	v_lshl_or_b32 v3, v3, 10, v16
	v_bfe_i32 v17, v1, 0, 16
	s_addc_u32 s31, s39, s5
	s_add_i32 s41, s40, 0
	v_add_lshl_u32 v152, v3, v17, 1
	s_add_i32 m0, s41, 0x10000
	v_mov_b32_e32 v153, v0
	global_load_lds_dwordx4 v152, s[30:31]
	s_add_i32 m0, s41, 0x12000
	s_add_u32 s4, s30, 0x40000
	global_load_lds_dwordx4 v150, s[30:31]
	s_addc_u32 s5, s31, 0
	s_add_i32 m0, s41, 0x14000
	v_mov_b32_e32 v151, v0
	global_load_lds_dwordx4 v152, s[4:5]
	s_add_i32 m0, s41, 0x16000
	v_lshl_add_u64 v[8:9], s[30:31], 0, v[152:153]
	global_load_lds_dwordx4 v150, s[4:5]
	v_readlane_b32 s4, v254, 58
	v_readlane_b32 s5, v254, 59
	s_add_u32 s28, s0, s4
	s_addc_u32 s29, s1, s5
	s_add_i32 s42, s41, 0x2000
	s_mov_b32 m0, s41
	s_add_u32 s4, s28, 0x40000
	global_load_lds_dwordx4 v152, s[28:29]
	s_mov_b32 m0, s42
	s_addc_u32 s5, s29, 0
	s_add_i32 s43, s41, 0x4000
	global_load_lds_dwordx4 v150, s[28:29]
	s_mov_b32 m0, s43
	s_add_i32 s44, s41, 0x6000
	global_load_lds_dwordx4 v152, s[4:5]
	s_mov_b32 m0, s44
	s_cmp_eq_u32 s8, 1
	global_load_lds_dwordx4 v150, s[4:5]
	v_lshl_add_u64 v[6:7], s[30:31], 0, v[150:151]
	v_lshl_add_u64 v[2:3], s[28:29], 0, v[152:153]
	s_cselect_b64 s[12:13], -1, 0
	s_cmp_lg_u32 s8, 1
	v_lshl_add_u64 v[4:5], s[28:29], 0, v[150:151]
	s_cbranch_scc1 .LBB0_1670
	s_barrier

; #define PG8_BAR __builtin_amdgcn_s_barrier()
; template <class Epi, class Sched, bool ALIGN_EPI = false, bool SP2 = false>
; __device__ __forceinline__ void gemm_phase(PG8_LAS unsigned char* lds, const Gemm g, const Sched& S, const Epi& E) {
;     int tid_l = pg8_tid(lds); asm volatile("" : "+v"(tid_l));
;     const int tid = tid_l, wid = __builtin_amdgcn_readfirstlane(tid >> 6), lane = tid & 63, wr = wid >> 2, wc = wid & 3, fr = lane & 15, fq = lane >> 4;
;     const int K = g.K, nt = K / BK;
;     unsigned voffA[2], voffB[2];
; #pragma unroll
;     for (int i = 0; i < 2; ++i) { int R, C; stage_rc(tid * 16 + i * 8192, R, C); const int Rb = Epi::PERM ? ((R & ~31) + perm32(R & 31)) : R;
;         voffA[i] = (unsigned)(R * K + C) * 2u; voffB[i] = (unsigned)(Rb * K + C) * 2u; }
;     const size_t kstep = (size_t)(BK * 2);
;     const size_t hstep = (size_t)HALF * K * 2;
;     const size_t tstep = 2 * hstep;
;     const unsigned ldsw = (unsigned)wid * 1024u;
;     const int aoff = lds_byte(wr * 64 + fr, fq * 8), boff = lds_byte(wc * 32 + fr, fq * 8);
;     ...
;     Unit cur, nxt; int ui = 0;
;     if (!S.next(0, cur)) return;
;     f32x4 acc[2][2][4][2];
; #pragma unroll
;     for (int a = 0; a < 2; ++a)
; #pragma unroll
;         for (int b = 0; b < 2; ++b)
; #pragma unroll
;             for (int m = 0; m < 4; ++m)
; #pragma unroll
;                 for (int n = 0; n < 2; ++n) acc[a][b][m][n] = (f32x4){0.f, 0.f, 0.f, 0.f};
;     bf16x8 At[4][2], B0[2][2], B1[2][2];
;     const char* cA = (const char*)g.A + (size_t)cur.pm * tstep; const char* cB = (const char*)g.Bt + (size_t)cur.pn * tstep;
;     S.a_ready(cur);
;     if constexpr (SP2) {
;         PG8_STAGE(PG8_SB(0, 0), cB, voffB); PG8_STAGE(PG8_SB(0, 1), cB + hstep, voffB); PG8_STAGE(PG8_SA(0, 0), cA, voffA); PG8_STAGE(PG8_SA(0, 1), cA + hstep, voffA);
;         if (wr == 1) PG8_BAR;
; __global__ void __launch_bounds__(512, 2) fwd_megakernel(Params p) {
;     ...
;         {
;             LWS(ws);
;             pg8::Gemm g{(const bf16_t*)(ws + WS_HID), (const bf16_t*)(ws + WS_WDN) + (size_t)l * DM * DFF, MP, DM, DFF}; pg8::StaticOrder S; S.init(MP, DM, G, bx);
;             EpiResid E{nullptr, (bf16_t*)(ws + WS_XB), (float*)(ws + WS_SSQA)};
;             pg8::gemm_phase<EpiResid, pg8::StaticOrder, true, true>(lds, g, S, E);
.LBB0_1873:
	s_or_b64 exec, exec, s[8:9]
	s_mov_b64 s[8:9], 0
	s_waitcnt lgkmcnt(0)
	s_barrier
	s_getreg_b32 s100, hwreg(HW_REG_XCC_ID, 0, 4)
	s_and_b32 s100, s100, 3
	s_mul_i32 s100, s100, 300
	s_memrealtime s[0:1]
	s_waitcnt lgkmcnt(0)
	s_add_u32 s100, s100, s0
.Lstagger_dn:
	s_memrealtime s[0:1]
	s_waitcnt lgkmcnt(0)
	s_sub_u32 s1, s100, s0
	s_cmp_gt_i32 s1, 0
	s_cbranch_scc1 .Lstagger_dn
	s_getreg_b32 s0, hwreg(HW_REG_HW_ID, 0, 6)
	s_and_b32 s0, s0, 63
	s_lshl_b32 s0, s0, 2
	s_add_i32 s0, s0, 0
	s_add_i32 s0, s0, 0x20100
	v_mov_b32_e32 v1, s0
	ds_read_b32 v1, v1
	s_and_b64 vcc, exec, s[6:7]
	s_waitcnt lgkmcnt(0)
	v_readfirstlane_b32 s0, v1
	s_nop 1
	v_lshl_add_u32 v18, s0, 6, v190
	s_nop 0
	v_readfirstlane_b32 s6, v18
	s_cbranch_vccnz .LBB0_1913
	v_lshlrev_b32_e32 v1, 4, v18
	v_add_u32_e32 v2, 0x2000, v1
	v_ashrrev_i32_e32 v3, 31, v2
	v_lshrrev_b32_e32 v3, 22, v3
	v_add_u32_e32 v3, v2, v3
	v_ashrrev_i32_e32 v10, 10, v3
	v_mul_i32_i24_e32 v3, 0x400, v10
	v_sub_u32_e32 v2, v2, v3
	v_lshrrev_b32_e32 v3, 4, v2
	v_bitop3_b32 v2, v3, v2, 32 bitop3:0x6c
	v_ashrrev_i32_e32 v3, 31, v2
	v_lshrrev_b32_e32 v3, 26, v3
	v_add_u32_e32 v3, v2, v3
	v_ashrrev_i32_e32 v11, 6, v3
	v_and_b32_e32 v3, 0xc0, v3
	v_sub_u32_e32 v2, v2, v3
	v_ashrrev_i16_sdwa v2, v197, sext(v2) dst_sel:DWORD dst_unused:UNUSED_PAD src0_sel:DWORD src1_sel:BYTE_0
	v_bfe_i32 v13, v2, 0, 16
	v_bfe_i32 v2, v18, 27, 1
	v_lshrrev_b32_e32 v2, 22, v2
	v_add_u32_e32 v2, v1, v2
	s_add_u32 s8, s58, s8
	v_and_b32_e32 v2, 0xfffffc00, v2
	s_addc_u32 s9, s59, s9
	v_sub_u32_e32 v1, v1, v2
	s_add_u32 s0, s8, 0x1c200000
	v_lshrrev_b32_e32 v2, 4, v1
	v_ashrrev_i32_e32 v3, 31, v18
	s_addc_u32 s1, s9, 0
	s_mul_i32 s4, s92, 0x580000
	v_lshlrev_b32_e32 v4, 3, v10
	v_bitop3_b32 v1, v2, v1, 32 bitop3:0x6c
	v_lshrrev_b32_e32 v3, 26, v3
	s_add_u32 s4, s8, s4
	v_and_b32_e32 v4, 0xfffff0, v4
	v_ashrrev_i32_e32 v2, 31, v1
	v_add_u32_e32 v3, v18, v3
	s_addc_u32 s5, s9, 0
	v_add_u32_e32 v4, v11, v4
	v_lshlrev_b32_e32 v5, 5, v10
	v_lshrrev_b32_e32 v2, 26, v2
	v_ashrrev_i32_e32 v15, 6, v3
	s_add_u32 s30, s4, 0x2200000
	v_mul_lo_u32 v4, v4, s94
	v_and_b32_e32 v12, 32, v5
	v_add_u32_e32 v2, v1, v2
	v_lshlrev_b32_e32 v3, 3, v15
	s_addc_u32 s31, s5, 0
	s_ashr_i32 s10, s6, 6
	v_or_b32_e32 v4, v4, v12
	v_ashrrev_i32_e32 v14, 6, v2
	v_and_b32_e32 v3, 0xfffff0, v3
	v_and_b32_e32 v2, 0xc0, v2
	v_readlane_b32 s5, v254, 48
	s_ashr_i32 s7, s6, 8
	s_lshl_b32 s34, s10, 10
	v_add_lshl_u32 v150, v4, v13, 1
	v_add_u32_e32 v3, v14, v3
	v_lshlrev_b32_e32 v4, 5, v15
	v_sub_u32_e32 v1, v1, v2
	s_mul_i32 s4, s5, 0x160000
	v_mul_lo_u32 v3, v3, s94
	v_and_b32_e32 v16, 32, v4
	v_ashrrev_i16_sdwa v1, v197, sext(v1) dst_sel:DWORD dst_unused:UNUSED_PAD src0_sel:DWORD src1_sel:BYTE_0
	s_add_u32 s24, s30, s4
	s_mul_hi_i32 s4, s5, 0x160000
	v_or_b32_e32 v3, v3, v16
	v_bfe_i32 v17, v1, 0, 16
	s_addc_u32 s25, s31, s4
	s_add_i32 s35, s34, 0
	v_add_lshl_u32 v152, v3, v17, 1
	s_add_i32 m0, s35, 0x10000
	v_mov_b32_e32 v153, v0
	global_load_lds_dwordx4 v152, s[24:25]
	s_add_i32 m0, s35, 0x12000
	s_add_u32 s4, s24, 0xb0000
	global_load_lds_dwordx4 v150, s[24:25]
	s_addc_u32 s5, s25, 0
	s_add_i32 m0, s35, 0x14000
	v_mov_b32_e32 v151, v0
	global_load_lds_dwordx4 v152, s[4:5]
	s_add_i32 m0, s35, 0x16000
	v_lshl_add_u64 v[8:9], s[24:25], 0, v[152:153]
	global_load_lds_dwordx4 v150, s[4:5]
	v_readlane_b32 s4, v254, 56
	s_mov_b32 s12, s4
	s_mul_i32 s4, s4, 0x160000
	s_add_u32 s22, s0, s4
	s_mul_hi_i32 s4, s12, 0x160000
	s_addc_u32 s23, s1, s4
	s_add_i32 s36, s35, 0x2000
	v_readlane_b32 s5, v254, 57
	s_mov_b32 m0, s35
	s_add_u32 s4, s22, 0xb0000
	global_load_lds_dwordx4 v152, s[22:23]
	s_mov_b32 m0, s36
	s_addc_u32 s5, s23, 0
	s_add_i32 s37, s35, 0x4000
	global_load_lds_dwordx4 v150, s[22:23]
	s_mov_b32 m0, s37
	s_add_i32 s38, s35, 0x6000
	global_load_lds_dwordx4 v152, s[4:5]
	s_mov_b32 m0, s38
	s_cmp_eq_u32 s7, 1
	global_load_lds_dwordx4 v150, s[4:5]
	v_lshl_add_u64 v[6:7], s[24:25], 0, v[150:151]
	v_lshl_add_u64 v[2:3], s[22:23], 0, v[152:153]
	s_cselect_b64 s[12:13], -1, 0
	s_cmp_lg_u32 s7, 1
	v_lshl_add_u64 v[4:5], s[22:23], 0, v[150:151]
	s_cbranch_scc1 .LBB0_1876
	s_barrier
